# P0 XN stores nt instead of sc1
# baseline (speedup 1.0000x reference)
.LBB0_97:
	s_waitcnt vmcnt(3)
	v_pk_mul_f32 v[90:91], v[78:79], v[78:79]
	v_pk_mul_f32 v[92:93], v[76:77], v[76:77]
	s_lshl_b64 s[20:21], s[20:21], 11
	v_pk_mov_b32 v[94:95], v[92:93], v[90:91] op_sel:[1,0]
	v_mov_b32_e32 v93, v91
	v_pk_add_f32 v[90:91], v[94:95], v[92:93]
	s_waitcnt vmcnt(2)
	v_pk_mul_f32 v[92:93], v[74:75], v[74:75]
	v_pk_mul_f32 v[94:95], v[72:73], v[72:73]
	v_pk_add_f32 v[90:91], v[90:91], v[90:91] op_sel:[0,1] op_sel_hi:[1,0]
	v_pk_mov_b32 v[96:97], v[94:95], v[92:93] op_sel:[1,0]
	v_mov_b32_e32 v95, v93
	v_pk_add_f32 v[92:93], v[96:97], v[94:95]
	s_waitcnt vmcnt(0)
	v_mul_f32_e32 v91, v64, v64
	v_pk_add_f32 v[92:93], v[92:93], v[92:93] op_sel:[0,1] op_sel_hi:[1,0]
	v_mul_f32_e32 v94, v71, v71
	v_mul_f32_e32 v93, v65, v65
	v_pk_add_f32 v[90:91], v[90:91], v[92:93]
	v_mul_f32_e32 v92, v69, v69
	v_pk_fma_f32 v[92:93], v[68:69], v[68:69], v[92:93] op_sel_hi:[1,1,0]
	v_pk_fma_f32 v[94:95], v[70:71], v[70:71], v[94:95] op_sel_hi:[1,1,0]
	v_mul_f32_e32 v93, v66, v66
	v_mul_f32_e32 v95, v67, v67
	v_pk_add_f32 v[92:93], v[92:93], v[94:95]
	v_mul_f32_e32 v94, v53, v53
	v_pk_add_f32 v[90:91], v[90:91], v[92:93]
	v_mul_f32_e32 v92, v61, v61
	v_add_f32_e32 v90, v90, v91
	ds_bpermute_b32 v91, v82, v90
	v_mul_f32_e32 v93, v63, v63
	v_fmac_f32_e32 v92, v60, v60
	v_fmac_f32_e32 v93, v62, v62
	v_fmac_f32_e32 v94, v52, v52
	s_waitcnt lgkmcnt(0)
	v_add_f32_e32 v90, v90, v91
	ds_bpermute_b32 v91, v83, v90
	s_andn2_b64 vcc, exec, s[18:19]
	s_waitcnt lgkmcnt(0)
	v_add_f32_e32 v90, v90, v91
	ds_bpermute_b32 v91, v84, v90
	s_waitcnt lgkmcnt(0)
	v_add_f32_e32 v90, v90, v91
	ds_bpermute_b32 v91, v85, v90
	s_waitcnt lgkmcnt(0)
	v_add_f32_e32 v90, v90, v91
	ds_bpermute_b32 v91, v86, v90
	s_waitcnt lgkmcnt(0)
	v_add_f32_e32 v90, v90, v91
	ds_bpermute_b32 v91, v87, v90
	s_waitcnt lgkmcnt(0)
	v_add_f32_e32 v90, v90, v91
	v_fmamk_f32 v90, v90, 0x3a800000, v89
	v_rsq_f32_e32 v90, v90
	v_add_f32_e32 v91, v92, v93
	v_mul_f32_e32 v92, v55, v55
	v_fmac_f32_e32 v92, v54, v54
	v_add_f32_e32 v92, v94, v92
	v_pk_mul_f32 v[76:77], v[90:91], v[76:77] op_sel_hi:[0,1]
	v_pk_mul_f32 v[78:79], v[90:91], v[78:79] op_sel_hi:[0,1]
	v_add_f32_e32 v91, v91, v92
	v_mul_f32_e32 v92, v45, v45
	v_mul_f32_e32 v93, v47, v47
	v_fmac_f32_e32 v92, v44, v44
	v_fmac_f32_e32 v93, v46, v46
	v_add_f32_e32 v92, v92, v93
	v_add_f32_e32 v91, v91, v92
	v_mul_f32_e32 v92, v33, v33
	v_mul_f32_e32 v93, v35, v35
	v_fmac_f32_e32 v92, v32, v32
	v_fmac_f32_e32 v93, v34, v34
	v_add_f32_e32 v92, v92, v93
	v_add_f32_e32 v91, v91, v92
	v_pk_mul_f32 v[78:79], v[78:79], v[2:3]
	v_pk_mul_f32 v[76:77], v[76:77], v[0:1]
	v_pk_mul_f32 v[72:73], v[90:91], v[72:73] op_sel_hi:[0,1]
	v_pk_mul_f32 v[74:75], v[90:91], v[74:75] op_sel_hi:[0,1]
	v_cvt_pk_bf16_f32 v76, v76, v77
	v_cvt_pk_bf16_f32 v77, v78, v79
	v_lshl_add_u64 v[78:79], v[80:81], 0, s[20:21]
	v_pk_mul_f32 v[74:75], v[74:75], v[6:7]
	v_pk_mul_f32 v[72:73], v[72:73], v[4:5]
	global_store_dwordx2 v[78:79], v[76:77], off nt
	s_nop 1
	v_mul_f32_e32 v76, v57, v57
	v_cvt_pk_bf16_f32 v72, v72, v73
	v_cvt_pk_bf16_f32 v73, v74, v75
	v_lshl_add_u64 v[74:75], v[78:79], 0, s[0:1]
	v_mul_f32_e32 v77, v59, v59
	global_store_dwordx2 v[74:75], v[72:73], off nt
	s_nop 1
	v_mul_f32_e32 v73, v17, v17
	v_mul_f32_e32 v74, v19, v19
	v_fmac_f32_e32 v76, v56, v56
	v_fmac_f32_e32 v77, v58, v58
	v_fmac_f32_e32 v73, v16, v16
	v_fmac_f32_e32 v74, v18, v18
	v_add_f32_e32 v76, v76, v77
	v_mul_f32_e32 v77, v49, v49
	v_mul_f32_e32 v92, v51, v51
	v_add_f32_e32 v73, v73, v74
	v_mul_f32_e32 v74, v41, v41
	v_mul_f32_e32 v75, v43, v43
	v_fmac_f32_e32 v77, v48, v48
	v_fmac_f32_e32 v92, v50, v50
	v_fmac_f32_e32 v74, v40, v40
	v_fmac_f32_e32 v75, v42, v42
	v_add_f32_e32 v77, v77, v92
	v_add_f32_e32 v74, v74, v75
	v_add_f32_e32 v76, v76, v77
	v_mul_f32_e32 v77, v37, v37
	v_mul_f32_e32 v92, v39, v39
	v_add_f32_e32 v73, v73, v74
	v_mul_f32_e32 v74, v29, v29
	v_mul_f32_e32 v75, v31, v31
	v_fmac_f32_e32 v77, v36, v36
	v_fmac_f32_e32 v92, v38, v38
	v_fmac_f32_e32 v74, v28, v28
	v_fmac_f32_e32 v75, v30, v30
	v_add_f32_e32 v77, v77, v92
	v_add_f32_e32 v74, v74, v75
	v_add_f32_e32 v76, v76, v77
	v_mul_f32_e32 v77, v25, v25
	v_mul_f32_e32 v92, v27, v27
	v_add_f32_e32 v73, v73, v74
	v_mul_f32_e32 v74, v21, v21
	v_mul_f32_e32 v75, v23, v23
	v_fmac_f32_e32 v77, v24, v24
	v_fmac_f32_e32 v92, v26, v26
	v_fmac_f32_e32 v74, v20, v20
	v_fmac_f32_e32 v75, v22, v22
	v_add_f32_e32 v77, v77, v92
	v_add_f32_e32 v74, v74, v75
	v_add_f32_e32 v76, v76, v77
	v_add_f32_e32 v73, v73, v74
	ds_bpermute_b32 v77, v82, v91
	ds_bpermute_b32 v72, v82, v76
	ds_bpermute_b32 v74, v82, v73
	s_waitcnt lgkmcnt(2)
	v_add_f32_e32 v75, v91, v77
	s_waitcnt lgkmcnt(1)
	v_add_f32_e32 v72, v76, v72
	s_waitcnt lgkmcnt(0)
	v_add_f32_e32 v73, v73, v74
	ds_bpermute_b32 v77, v83, v75
	ds_bpermute_b32 v76, v83, v72
	ds_bpermute_b32 v74, v83, v73
	s_waitcnt lgkmcnt(2)
	v_add_f32_e32 v75, v75, v77
	s_waitcnt lgkmcnt(1)
	v_add_f32_e32 v72, v72, v76
	s_waitcnt lgkmcnt(0)
	v_add_f32_e32 v73, v73, v74
	ds_bpermute_b32 v77, v84, v75
	ds_bpermute_b32 v76, v84, v72
	ds_bpermute_b32 v74, v84, v73
	s_waitcnt lgkmcnt(2)
	v_add_f32_e32 v75, v75, v77
	s_waitcnt lgkmcnt(1)
	v_add_f32_e32 v72, v72, v76
	s_waitcnt lgkmcnt(0)
	v_add_f32_e32 v73, v73, v74
	ds_bpermute_b32 v77, v85, v75
	ds_bpermute_b32 v76, v85, v72
	ds_bpermute_b32 v74, v85, v73
	s_waitcnt lgkmcnt(2)
	v_add_f32_e32 v75, v75, v77
	s_waitcnt lgkmcnt(1)
	v_add_f32_e32 v72, v72, v76
	s_waitcnt lgkmcnt(0)
	v_add_f32_e32 v92, v73, v74
	ds_bpermute_b32 v77, v86, v75
	ds_bpermute_b32 v91, v86, v72
	ds_bpermute_b32 v93, v86, v92
	s_waitcnt lgkmcnt(2)
	v_add_f32_e32 v75, v75, v77
	s_waitcnt lgkmcnt(1)
	v_add_f32_e32 v73, v72, v91
	s_waitcnt lgkmcnt(0)
	v_add_f32_e32 v72, v92, v93
	v_pk_mul_f32 v[92:93], v[90:91], v[68:69] op_sel_hi:[0,1]
	v_pk_mul_f32 v[70:71], v[90:91], v[70:71] op_sel_hi:[0,1]
	ds_bpermute_b32 v76, v87, v75
	ds_bpermute_b32 v74, v87, v73
	ds_bpermute_b32 v68, v87, v72
	v_pk_mul_f32 v[70:71], v[70:71], v[10:11]
	v_pk_mul_f32 v[92:93], v[92:93], v[8:9]
	v_pk_mul_f32 v[64:65], v[90:91], v[64:65] op_sel_hi:[0,1]
	v_cvt_pk_bf16_f32 v92, v92, v93
	v_cvt_pk_bf16_f32 v93, v70, v71
	v_lshl_add_u64 v[70:71], v[78:79], 0, s[4:5]
	v_pk_mul_f32 v[66:67], v[90:91], v[66:67] op_sel_hi:[0,1]
	v_pk_mul_f32 v[64:65], v[64:65], v[12:13]
	global_store_dwordx2 v[70:71], v[92:93], off nt
	s_nop 1
	v_pk_mul_f32 v[66:67], v[66:67], v[14:15]
	v_lshl_add_u64 v[70:71], v[78:79], 0, s[6:7]
	v_cvt_pk_bf16_f32 v64, v64, v65
	v_cvt_pk_bf16_f32 v65, v66, v67
	s_nop 0
	global_store_dwordx2 v[70:71], v[64:65], off nt
	s_nop 1
	s_cbranch_vccz .LBB0_100
	s_andn2_b64 vcc, exec, s[16:17]
	s_cbranch_vccz .LBB0_101

.LBB0_100:
	s_waitcnt lgkmcnt(2)
	v_add_f32_e32 v64, v75, v76
	v_fmamk_f32 v64, v64, 0x3a800000, v89
	v_rsq_f32_e32 v64, v64
	s_ashr_i32 s13, s12, 31
	s_lshl_b64 s[12:13], s[12:13], 11
	v_lshl_add_u64 v[66:67], v[80:81], 0, s[12:13]
	v_pk_mul_f32 v[60:61], v[64:65], v[60:61] op_sel_hi:[0,1]
	v_pk_mul_f32 v[62:63], v[64:65], v[62:63] op_sel_hi:[0,1]
	v_pk_mul_f32 v[60:61], v[60:61], v[0:1]
	v_pk_mul_f32 v[52:53], v[64:65], v[52:53] op_sel_hi:[0,1]
	v_pk_mul_f32 v[44:45], v[64:65], v[44:45] op_sel_hi:[0,1]
	v_pk_mul_f32 v[62:63], v[62:63], v[2:3]
	v_cvt_pk_bf16_f32 v60, v60, v61
	v_pk_mul_f32 v[54:55], v[64:65], v[54:55] op_sel_hi:[0,1]
	v_cvt_pk_bf16_f32 v61, v62, v63
	v_pk_mul_f32 v[52:53], v[52:53], v[4:5]
	v_pk_mul_f32 v[46:47], v[64:65], v[46:47] op_sel_hi:[0,1]
	v_pk_mul_f32 v[44:45], v[44:45], v[8:9]
	v_pk_mul_f32 v[32:33], v[64:65], v[32:33] op_sel_hi:[0,1]
	global_store_dwordx2 v[66:67], v[60:61], off nt
	s_nop 1
	v_pk_mul_f32 v[54:55], v[54:55], v[6:7]
	v_lshl_add_u64 v[60:61], v[66:67], 0, s[0:1]
	v_cvt_pk_bf16_f32 v52, v52, v53
	v_cvt_pk_bf16_f32 v53, v54, v55
	v_pk_mul_f32 v[46:47], v[46:47], v[10:11]
	global_store_dwordx2 v[60:61], v[52:53], off nt
	s_nop 1
	v_cvt_pk_bf16_f32 v44, v44, v45
	v_pk_mul_f32 v[34:35], v[64:65], v[34:35] op_sel_hi:[0,1]
	v_cvt_pk_bf16_f32 v45, v46, v47
	v_pk_mul_f32 v[32:33], v[32:33], v[12:13]
	v_lshl_add_u64 v[52:53], v[66:67], 0, s[4:5]
	global_store_dwordx2 v[52:53], v[44:45], off nt
	s_nop 1
	v_pk_mul_f32 v[34:35], v[34:35], v[14:15]
	v_lshl_add_u64 v[44:45], v[66:67], 0, s[6:7]
	v_cvt_pk_bf16_f32 v32, v32, v33
	v_cvt_pk_bf16_f32 v33, v34, v35
	s_nop 0
	global_store_dwordx2 v[44:45], v[32:33], off nt
	s_nop 1
	s_andn2_b64 vcc, exec, s[16:17]
	s_cbranch_vccnz .LBB0_99
.LBB0_101:
	s_waitcnt lgkmcnt(1)
	v_add_f32_e32 v32, v73, v74
	v_fmamk_f32 v32, v32, 0x3a800000, v89
	v_rsq_f32_e32 v32, v32
	s_ashr_i32 s11, s10, 31
	s_lshl_b64 s[10:11], s[10:11], 11
	v_lshl_add_u64 v[34:35], v[80:81], 0, s[10:11]
	v_pk_mul_f32 v[44:45], v[32:33], v[56:57] op_sel_hi:[0,1]
	v_pk_mul_f32 v[46:47], v[32:33], v[58:59] op_sel_hi:[0,1]
	v_pk_mul_f32 v[44:45], v[44:45], v[0:1]
	v_pk_mul_f32 v[46:47], v[46:47], v[2:3]
	v_cvt_pk_bf16_f32 v44, v44, v45
	v_pk_mul_f32 v[36:37], v[32:33], v[36:37] op_sel_hi:[0,1]
	v_cvt_pk_bf16_f32 v45, v46, v47
	v_pk_mul_f32 v[46:47], v[32:33], v[50:51] op_sel_hi:[0,1]
	global_store_dwordx2 v[34:35], v[44:45], off nt
	s_nop 1
	v_pk_mul_f32 v[44:45], v[32:33], v[48:49] op_sel_hi:[0,1]
	v_pk_mul_f32 v[44:45], v[44:45], v[4:5]
	v_pk_mul_f32 v[24:25], v[32:33], v[24:25] op_sel_hi:[0,1]
	v_pk_mul_f32 v[46:47], v[46:47], v[6:7]
	v_cvt_pk_bf16_f32 v44, v44, v45
	v_pk_mul_f32 v[38:39], v[32:33], v[38:39] op_sel_hi:[0,1]
	v_cvt_pk_bf16_f32 v45, v46, v47
	v_pk_mul_f32 v[36:37], v[36:37], v[8:9]
	v_pk_mul_f32 v[26:27], v[32:33], v[26:27] op_sel_hi:[0,1]
	v_pk_mul_f32 v[24:25], v[24:25], v[12:13]
	v_lshl_add_u64 v[48:49], v[34:35], 0, s[0:1]
	global_store_dwordx2 v[48:49], v[44:45], off nt
	s_nop 1
	v_pk_mul_f32 v[38:39], v[38:39], v[10:11]
	v_lshl_add_u64 v[44:45], v[34:35], 0, s[4:5]
	v_cvt_pk_bf16_f32 v36, v36, v37
	v_cvt_pk_bf16_f32 v37, v38, v39
	v_pk_mul_f32 v[26:27], v[26:27], v[14:15]
	global_store_dwordx2 v[44:45], v[36:37], off nt
	s_nop 1
	v_lshl_add_u64 v[32:33], v[34:35], 0, s[6:7]
	v_cvt_pk_bf16_f32 v24, v24, v25
	v_cvt_pk_bf16_f32 v25, v26, v27
	s_nop 0
	global_store_dwordx2 v[32:33], v[24:25], off nt
	s_nop 1
	s_andn2_b64 vcc, exec, s[14:15]
	s_cbranch_vccnz .LBB0_90
.LBB0_102:
	s_waitcnt lgkmcnt(0)
	v_add_f32_e32 v24, v72, v68
	v_fmamk_f32 v24, v24, 0x3a800000, v89
	v_rsq_f32_e32 v24, v24
	s_ashr_i32 s9, s8, 31
	s_lshl_b64 s[8:9], s[8:9], 11
	v_lshl_add_u64 v[26:27], v[80:81], 0, s[8:9]
	v_pk_mul_f32 v[16:17], v[24:25], v[16:17] op_sel_hi:[0,1]
	v_pk_mul_f32 v[18:19], v[24:25], v[18:19] op_sel_hi:[0,1]
	v_pk_mul_f32 v[16:17], v[16:17], v[0:1]
	v_pk_mul_f32 v[18:19], v[18:19], v[2:3]
	v_cvt_pk_bf16_f32 v16, v16, v17
	v_lshl_add_u64 v[32:33], v[26:27], 0, s[0:1]
	v_cvt_pk_bf16_f32 v17, v18, v19
	v_pk_mul_f32 v[18:19], v[24:25], v[42:43] op_sel_hi:[0,1]
	global_store_dwordx2 v[26:27], v[16:17], off nt
	s_nop 1
	v_pk_mul_f32 v[16:17], v[24:25], v[40:41] op_sel_hi:[0,1]
	v_pk_mul_f32 v[16:17], v[16:17], v[4:5]
	v_pk_mul_f32 v[18:19], v[18:19], v[6:7]
	v_cvt_pk_bf16_f32 v16, v16, v17
	s_nop 0
	v_cvt_pk_bf16_f32 v17, v18, v19
	v_pk_mul_f32 v[18:19], v[24:25], v[30:31] op_sel_hi:[0,1]
	global_store_dwordx2 v[32:33], v[16:17], off nt
	s_nop 1
	v_pk_mul_f32 v[16:17], v[24:25], v[28:29] op_sel_hi:[0,1]
	v_pk_mul_f32 v[16:17], v[16:17], v[8:9]
	v_pk_mul_f32 v[18:19], v[18:19], v[10:11]
	v_cvt_pk_bf16_f32 v16, v16, v17
	v_lshl_add_u64 v[28:29], v[26:27], 0, s[4:5]
	v_cvt_pk_bf16_f32 v17, v18, v19
	v_pk_mul_f32 v[18:19], v[24:25], v[22:23] op_sel_hi:[0,1]
	global_store_dwordx2 v[28:29], v[16:17], off nt
	s_nop 1
	v_pk_mul_f32 v[16:17], v[24:25], v[20:21] op_sel_hi:[0,1]
	v_pk_mul_f32 v[16:17], v[16:17], v[12:13]
	v_pk_mul_f32 v[18:19], v[18:19], v[14:15]
	v_lshl_add_u64 v[20:21], v[26:27], 0, s[6:7]
	v_cvt_pk_bf16_f32 v16, v16, v17
	v_cvt_pk_bf16_f32 v17, v18, v19
	s_nop 0
	global_store_dwordx2 v[20:21], v[16:17], off nt
	s_nop 1
	s_branch .LBB0_90
